# PAIR epilogue: rstd partials + bias prefetched by LDS-DMA at unit start; unit-start vmcnt(0) removed
# baseline (speedup 1.0000x reference)
.LBB0_459:
	s_barrier
	s_lshl_b32 s4, s29, 1
	s_lshl_b32 s26, s46, 14
	v_lshlrev_b32_e32 v3, 4, v227
	s_add_u32 s26, s76, s26
	s_addc_u32 s27, s77, 0
	v_add_u32_e32 v2, s4, v3
	s_add_i32 m0, s4, 0x21000
	s_ashr_i32 s5, s46, 5
	global_load_lds_dwordx4 v2, s[26:27]
	global_load_lds_dwordx4 v2, s[26:27] offset:1024
	s_mul_i32 s5, s5, s2
	s_lshl_b32 s4, s42, 8
	s_add_i32 s5, s5, s4
	s_lshl_b32 s5, s5, 2
	s_add_u32 s26, s43, s5
	s_addc_u32 s27, s52, 0
	s_mov_b32 m0, 0x25000
	s_nop 0
	global_load_lds_dwordx4 v3, s[26:27]
	s_add_i32 s61, s61, 1
	s_mul_i32 s4, s61, s63
	s_mul_hi_u32 s5, s61, s56
	s_add_i32 s5, s5, s4
	s_mul_i32 s4, s61, s56
	s_add_u32 s26, s4, s55
	s_addc_u32 s27, s5, s66
	v_mov_b64_e32 v[2:3], s[8:9]
	v_cmp_ge_i64_e32 vcc, s[26:27], v[2:3]
	v_cmp_lt_i64_e64 s[4:5], s[26:27], v[2:3]
	s_cbranch_vccnz .LBB0_461
	s_ashr_i32 s16, s26, 31
	s_lshr_b32 s16, s16, 29
	s_add_i32 s16, s26, s16
	s_ashr_i32 s17, s16, 3
	s_and_b32 s16, s16, -8
	s_sub_i32 s16, s26, s16
	s_lshr_b32 s18, s16, 31
	s_or_b32 s18, s69, s18
	s_mul_i32 s16, s18, s16
	s_add_i32 s16, s16, s17
	s_abs_i32 s18, s16
	s_mul_hi_u32 s19, s18, s72
	s_mul_i32 s24, s19, s67
	s_ashr_i32 s17, s16, 31
	s_sub_i32 s18, s18, s24
	s_xor_b32 s17, s17, s71
	s_add_i32 s24, s19, 1
	s_sub_i32 s26, s18, s67
	s_cmp_ge_u32 s18, s67
	s_cselect_b32 s19, s24, s19
	s_cselect_b32 s18, s26, s18
	s_add_i32 s24, s19, 1
	s_cmp_ge_u32 s18, s67
	s_cselect_b32 s18, s24, s19
	s_xor_b32 s18, s18, s17
	s_sub_i32 s17, s18, s17
	s_lshl_b32 s18, s17, 3
	s_sub_i32 s19, 0x80, s18
	s_min_i32 s19, s19, 8
	s_abs_i32 s24, s19
	v_cvt_f32_u32_e32 v2, s24
	s_sub_i32 s27, 0, s24
	s_mul_i32 s17, s17, s3
	s_sub_i32 s17, s16, s17
	v_rcp_iflag_f32_e32 v2, v2
	s_abs_i32 s26, s17
	s_xor_b32 s16, s17, s19
	s_ashr_i32 s16, s16, 31
	v_mul_f32_e32 v2, 0x4f7ffffe, v2
	v_cvt_u32_f32_e32 v2, v2
	s_nop 0
	v_readfirstlane_b32 s44, v2
	s_mul_i32 s27, s27, s44
	s_mul_hi_u32 s27, s44, s27
	s_add_i32 s44, s44, s27
	s_mul_hi_u32 s27, s26, s44
	s_mul_i32 s44, s27, s24
	s_sub_i32 s26, s26, s44
	s_add_i32 s44, s27, 1
	s_sub_i32 s45, s26, s24
	s_cmp_ge_u32 s26, s24
	s_cselect_b32 s27, s44, s27
	s_cselect_b32 s26, s45, s26
	s_add_i32 s44, s27, 1
	s_cmp_ge_u32 s26, s24
	s_cselect_b32 s24, s44, s27
	s_xor_b32 s24, s24, s16
	s_sub_i32 s16, s24, s16
	s_mul_i32 s19, s16, s19
	s_sub_i32 s17, s17, s19
	s_add_i32 s18, s17, s18
.LBB0_461:
	s_ashr_i32 s19, s18, 31
	s_lshl_b64 s[26:27], s[18:19], 19
	s_add_u32 s26, s58, s26
	s_addc_u32 s27, s59, s27
	s_and_b64 s[44:45], s[4:5], exec
	s_cselect_b32 s19, s27, s51
	s_cselect_b32 s24, s26, s50
	s_ashr_i32 s17, s16, 31
	s_lshl_b64 s[44:45], s[16:17], 19
	s_add_u32 s44, s13, s44
	s_addc_u32 s45, s21, s45
	s_and_b64 s[48:49], s[4:5], exec
	s_cselect_b32 s17, s45, s1
	s_cselect_b32 s47, s44, s0
	s_add_u32 s48, s0, 0x100
	s_addc_u32 s49, s1, 0
	s_add_u32 s0, s50, 0xc000
	v_mov_b32_e32 v2, 0
	s_addc_u32 s1, s51, 0
	s_mov_b32 s82, -2
	v_mov_b32_e32 v3, v2
	v_mov_b32_e32 v4, v2
	v_mov_b32_e32 v5, v2
	v_mov_b32_e32 v6, v2
	v_mov_b32_e32 v7, v2
	v_mov_b32_e32 v8, v2
	v_mov_b32_e32 v9, v2
	v_mov_b32_e32 v18, v2
	v_mov_b32_e32 v19, v2
	v_mov_b32_e32 v20, v2
	v_mov_b32_e32 v21, v2
	v_mov_b32_e32 v22, v2
	v_mov_b32_e32 v23, v2
	v_mov_b32_e32 v24, v2
	v_mov_b32_e32 v25, v2
	v_mov_b32_e32 v34, v2
	v_mov_b32_e32 v35, v2
	v_mov_b32_e32 v36, v2
	v_mov_b32_e32 v37, v2
	v_mov_b32_e32 v38, v2
	v_mov_b32_e32 v39, v2
	v_mov_b32_e32 v40, v2
	v_mov_b32_e32 v41, v2
	v_mov_b32_e32 v50, v2
	v_mov_b32_e32 v51, v2
	v_mov_b32_e32 v52, v2
	v_mov_b32_e32 v53, v2
	v_mov_b32_e32 v54, v2
	v_mov_b32_e32 v55, v2
	v_mov_b32_e32 v56, v2
	v_mov_b32_e32 v57, v2
	v_mov_b32_e32 v10, v2
	v_mov_b32_e32 v11, v2
	v_mov_b32_e32 v12, v2
	v_mov_b32_e32 v13, v2
	v_mov_b32_e32 v14, v2
	v_mov_b32_e32 v15, v2
	v_mov_b32_e32 v16, v2
	v_mov_b32_e32 v17, v2
	v_mov_b32_e32 v26, v2
	v_mov_b32_e32 v27, v2
	v_mov_b32_e32 v28, v2
	v_mov_b32_e32 v29, v2
	v_mov_b32_e32 v30, v2
	v_mov_b32_e32 v31, v2
	v_mov_b32_e32 v32, v2
	v_mov_b32_e32 v33, v2
	v_mov_b32_e32 v42, v2
	v_mov_b32_e32 v43, v2
	v_mov_b32_e32 v44, v2
	v_mov_b32_e32 v45, v2
	v_mov_b32_e32 v46, v2
	v_mov_b32_e32 v47, v2
	v_mov_b32_e32 v48, v2
	v_mov_b32_e32 v49, v2
	v_mov_b32_e32 v58, v2
	v_mov_b32_e32 v59, v2
	v_mov_b32_e32 v60, v2
	v_mov_b32_e32 v61, v2
	v_mov_b32_e32 v62, v2
	v_mov_b32_e32 v63, v2
	v_mov_b32_e32 v64, v2
	v_mov_b32_e32 v65, v2
	v_mov_b32_e32 v66, v2
	v_mov_b32_e32 v67, v2
	v_mov_b32_e32 v68, v2
	v_mov_b32_e32 v69, v2
	v_mov_b32_e32 v70, v2
	v_mov_b32_e32 v71, v2
	v_mov_b32_e32 v72, v2
	v_mov_b32_e32 v73, v2
	v_mov_b32_e32 v98, v2
	v_mov_b32_e32 v99, v2
	v_mov_b32_e32 v100, v2
	v_mov_b32_e32 v101, v2
	v_mov_b32_e32 v102, v2
	v_mov_b32_e32 v103, v2
	v_mov_b32_e32 v104, v2
	v_mov_b32_e32 v105, v2
	v_mov_b32_e32 v114, v2
	v_mov_b32_e32 v115, v2
	v_mov_b32_e32 v116, v2
	v_mov_b32_e32 v117, v2
	v_mov_b32_e32 v118, v2
	v_mov_b32_e32 v119, v2
	v_mov_b32_e32 v120, v2
	v_mov_b32_e32 v121, v2
	v_mov_b32_e32 v130, v2
	v_mov_b32_e32 v131, v2
	v_mov_b32_e32 v132, v2
	v_mov_b32_e32 v133, v2
	v_mov_b32_e32 v134, v2
	v_mov_b32_e32 v135, v2
	v_mov_b32_e32 v136, v2
	v_mov_b32_e32 v137, v2
	v_mov_b32_e32 v74, v2
	v_mov_b32_e32 v75, v2
	v_mov_b32_e32 v76, v2
	v_mov_b32_e32 v77, v2
	v_mov_b32_e32 v78, v2
	v_mov_b32_e32 v79, v2
	v_mov_b32_e32 v80, v2
	v_mov_b32_e32 v81, v2
	v_mov_b32_e32 v106, v2
	v_mov_b32_e32 v107, v2
	v_mov_b32_e32 v108, v2
	v_mov_b32_e32 v109, v2
	v_mov_b32_e32 v110, v2
	v_mov_b32_e32 v111, v2
	v_mov_b32_e32 v112, v2
	v_mov_b32_e32 v113, v2
	v_mov_b32_e32 v122, v2
	v_mov_b32_e32 v123, v2
	v_mov_b32_e32 v124, v2
	v_mov_b32_e32 v125, v2
	v_mov_b32_e32 v126, v2
	v_mov_b32_e32 v127, v2
	v_mov_b32_e32 v128, v2
	v_mov_b32_e32 v129, v2
	v_mov_b32_e32 v138, v2
	v_mov_b32_e32 v139, v2
	v_mov_b32_e32 v140, v2
	v_mov_b32_e32 v141, v2
	v_mov_b32_e32 v142, v2
	v_mov_b32_e32 v143, v2
	v_mov_b32_e32 v144, v2
	v_mov_b32_e32 v145, v2

.LBB0_465:
	v_and_b32_e32 v246, 0x60, v171
	v_lshrrev_b32_e32 v246, 1, v246
	v_lshl_add_u32 v246, v1, 6, v246
	v_add_u32_e32 v247, 0x25000, v171
	v_add_u32_e32 v246, 0x21000, v246
	s_lshl_b32 s17, s46, 8
	v_add_u32_e32 v178, s17, v1
	v_ashrrev_i32_e32 v179, 31, v178
	v_or_b32_e32 v202, 16, v178
	v_lshlrev_b64 v[82:83], 6, v[178:179]
	v_ashrrev_i32_e32 v203, 31, v202
	v_or_b32_e32 v188, 32, v178
	v_lshl_add_u64 v[82:83], v[158:159], 0, v[82:83]
	v_lshlrev_b64 v[84:85], 6, v[202:203]
	v_ashrrev_i32_e32 v189, 31, v188
	v_or_b32_e32 v184, 48, v178
	v_lshl_add_u64 v[84:85], v[158:159], 0, v[84:85]
	ds_read_b128 v[172:175], v246
	ds_read_b128 v[180:183], v246 offset:1024
	v_lshlrev_b64 v[82:83], 6, v[188:189]
	v_ashrrev_i32_e32 v185, 31, v184
	v_lshl_add_u64 v[82:83], v[158:159], 0, v[82:83]
	v_lshlrev_b64 v[84:85], 6, v[184:185]
	v_add_u32_e32 v168, 0x80, v178
	v_lshl_add_u64 v[84:85], v[158:159], 0, v[84:85]
	ds_read_b128 v[204:207], v246 offset:2048
	ds_read_b128 v[208:211], v246 offset:3072
	v_ashrrev_i32_e32 v169, 31, v168
	v_lshlrev_b64 v[82:83], 6, v[168:169]
	v_lshl_add_u64 v[82:83], v[158:159], 0, v[82:83]
	ds_read_b128 v[212:215], v246 offset:8192
	v_add_u32_e32 v82, 0x90, v178
	v_ashrrev_i32_e32 v83, 31, v82
	v_lshlrev_b64 v[82:83], 6, v[82:83]
	v_lshl_add_u64 v[82:83], v[158:159], 0, v[82:83]
	ds_read_b128 v[216:219], v246 offset:9216
	v_add_u32_e32 v82, 0xa0, v178
	v_ashrrev_i32_e32 v83, 31, v82
	v_add_u32_e32 v84, 0xb0, v178
	v_lshlrev_b64 v[82:83], 6, v[82:83]
	v_lshl_add_u64 v[82:83], v[158:159], 0, v[82:83]
	v_ashrrev_i32_e32 v85, 31, v84
	ds_read_b128 v[220:223], v246 offset:10240
	v_lshlrev_b64 v[82:83], 6, v[84:85]
	v_lshl_add_u64 v[82:83], v[158:159], 0, v[82:83]
	ds_read_b128 v[242:245], v246 offset:11264
	s_ashr_i32 s0, s46, 5
	s_mul_hi_i32 s1, s0, s2
	s_mul_i32 s0, s0, s2
	s_lshl_b64 s[0:1], s[0:1], 2
	s_add_u32 s19, s43, s0
	s_addc_u32 s24, s52, s1
	s_lshl_b32 s0, s42, 8
	s_ashr_i32 s1, s0, 31
	v_and_b32_e32 v83, 64, v227
	s_lshl_b64 s[0:1], s[0:1], 2
	v_xor_b32_e32 v82, 16, v227
	v_add_u32_e32 v166, 64, v83
	s_add_u32 s0, s19, s0
	v_cmp_lt_i32_e32 vcc, v82, v166
	s_addc_u32 s1, s24, s1
	v_xor_b32_e32 v164, 32, v227
	v_cndmask_b32_e32 v170, v227, v82, vcc
	ds_read_b128 v[90:93], v247 offset:16
	ds_read_b128 v[94:97], v247
	ds_read_b128 v[82:85], v247 offset:528
	ds_read_b128 v[86:89], v247 offset:512
	v_cmp_lt_i32_e32 vcc, v164, v166
	v_lshlrev_b32_e32 v166, 2, v170
	s_cmp_ge_i32 s42, s37
	v_cndmask_b32_e32 v164, v227, v164, vcc
	v_lshlrev_b32_e32 v164, 2, v164
	s_mov_b64 s[0:1], -1
	s_waitcnt lgkmcnt(0)
	v_add_f32_e32 v170, v172, v173
	v_add_f32_e32 v172, v174, v175
	v_add_f32_e32 v170, v170, v172
	v_add_f32_e32 v172, v180, v181
	v_add_f32_e32 v173, v182, v183
	ds_bpermute_b32 v182, v166, v170
	v_add_f32_e32 v172, v172, v173
	v_add_f32_e32 v174, v204, v205
	v_add_f32_e32 v175, v206, v207
	v_add_f32_e32 v176, v208, v209
	v_add_f32_e32 v177, v210, v211
	v_add_f32_e32 v173, v174, v175
	v_add_f32_e32 v174, v176, v177
	ds_bpermute_b32 v176, v166, v172
	ds_bpermute_b32 v177, v166, v173
	v_add_f32_e32 v180, v212, v213
	v_add_f32_e32 v181, v214, v215
	v_add_f32_e32 v175, v180, v181
	ds_bpermute_b32 v180, v166, v174
	s_waitcnt lgkmcnt(3)
	v_add_f32_e32 v170, v170, v182
	ds_bpermute_b32 v182, v164, v170
	s_waitcnt lgkmcnt(3)
	v_add_f32_e32 v172, v172, v176
	s_waitcnt lgkmcnt(2)
	v_add_f32_e32 v173, v173, v177
	ds_bpermute_b32 v176, v164, v172
	ds_bpermute_b32 v177, v164, v173
	ds_bpermute_b32 v181, v166, v175
	s_waitcnt lgkmcnt(4)
	v_add_f32_e32 v174, v174, v180
	ds_bpermute_b32 v183, v164, v174
	s_waitcnt lgkmcnt(4)
	v_add_f32_e32 v170, v170, v182
	v_fmamk_f32 v170, v170, 0x3a800000, v224
	s_waitcnt lgkmcnt(3)
	v_add_f32_e32 v172, v172, v176
	s_waitcnt lgkmcnt(2)
	v_add_f32_e32 v173, v173, v177
	v_rsq_f32_e32 v182, v170
	v_fmamk_f32 v170, v172, 0x3a800000, v224
	v_fmamk_f32 v172, v173, 0x3a800000, v224
	v_rsq_f32_e32 v176, v172
	s_waitcnt lgkmcnt(1)
	v_add_f32_e32 v172, v175, v181
	v_rsq_f32_e32 v180, v170
	s_waitcnt lgkmcnt(0)
	v_add_f32_e32 v170, v174, v183
	ds_bpermute_b32 v173, v164, v172
	v_add_f32_e32 v174, v216, v217
	v_add_f32_e32 v175, v218, v219
	v_add_f32_e32 v175, v174, v175
	ds_bpermute_b32 v177, v166, v175
	v_fmamk_f32 v170, v170, 0x3a800000, v224
	v_rsq_f32_e32 v174, v170
	s_waitcnt lgkmcnt(1)
	v_add_f32_e32 v170, v172, v173
	v_fmamk_f32 v170, v170, 0x3a800000, v224
	v_rsq_f32_e32 v172, v170
	s_waitcnt lgkmcnt(0)
	v_add_f32_e32 v170, v175, v177
	v_add_f32_e32 v175, v220, v221
	v_add_f32_e32 v177, v222, v223
	v_add_f32_e32 v181, v242, v243
	v_add_f32_e32 v183, v244, v245
	v_add_f32_e32 v175, v175, v177
	v_add_f32_e32 v181, v181, v183
	ds_bpermute_b32 v173, v164, v170
	ds_bpermute_b32 v177, v166, v175
	ds_bpermute_b32 v166, v166, v181
	s_waitcnt lgkmcnt(2)
	v_add_f32_e32 v170, v170, v173
	s_waitcnt lgkmcnt(1)
	v_add_f32_e32 v173, v175, v177
	s_waitcnt lgkmcnt(0)
	v_add_f32_e32 v177, v181, v166
	ds_bpermute_b32 v175, v164, v173
	ds_bpermute_b32 v164, v164, v177
	v_fmamk_f32 v170, v170, 0x3a800000, v224
	v_rsq_f32_e32 v170, v170
	s_waitcnt lgkmcnt(1)
	v_add_f32_e32 v166, v173, v175
	s_waitcnt lgkmcnt(0)
	v_add_f32_e32 v164, v177, v164
	v_fmamk_f32 v166, v166, 0x3a800000, v224
	v_fmamk_f32 v164, v164, 0x3a800000, v224
	v_rsq_f32_e32 v166, v166
	v_rsq_f32_e32 v164, v164
	s_cbranch_scc0 .LBB0_468
	s_sub_i32 s0, s42, s37
	s_lshl_b32 s24, s0, 8
	v_pk_fma_f32 v[186:187], v[144:145], v[182:183], v[96:97] op_sel_hi:[1,0,1]
	v_pk_fma_f32 v[204:205], v[142:143], v[182:183], v[94:95] op_sel_hi:[1,0,1]
	v_lshl_add_u64 v[208:209], s[24:25], 1, v[154:155]
	v_pk_fma_f32 v[206:207], v[138:139], v[182:183], v[90:91] op_sel_hi:[1,0,1]
	v_cvt_pk_bf16_f32 v204, v204, v205
	v_cvt_pk_bf16_f32 v205, v186, v187
	v_lshlrev_b64 v[186:187], 11, v[178:179]
	v_pk_fma_f32 v[210:211], v[140:141], v[182:183], v[92:93] op_sel_hi:[1,0,1]
	v_cvt_pk_bf16_f32 v206, v206, v207
	v_lshl_add_u64 v[186:187], v[208:209], 0, v[186:187]
	v_cvt_pk_bf16_f32 v207, v210, v211
	global_store_dwordx4 v[186:187], v[204:207], off
	v_pk_fma_f32 v[210:211], v[132:133], v[182:183], v[84:85] op_sel_hi:[1,0,1]
	v_pk_fma_f32 v[212:213], v[130:131], v[182:183], v[82:83] op_sel_hi:[1,0,1]
	v_pk_fma_f32 v[206:207], v[136:137], v[182:183], v[88:89] op_sel_hi:[1,0,1]
	v_pk_fma_f32 v[204:205], v[134:135], v[182:183], v[86:87] op_sel_hi:[1,0,1]
	v_lshlrev_b64 v[202:203], 11, v[202:203]
	v_cvt_pk_bf16_f32 v204, v204, v205
	v_cvt_pk_bf16_f32 v205, v206, v207
	v_cvt_pk_bf16_f32 v206, v212, v213
	v_cvt_pk_bf16_f32 v207, v210, v211
	global_store_dwordx4 v[186:187], v[204:207], off offset:256
	v_pk_fma_f32 v[210:211], v[124:125], v[180:181], v[92:93] op_sel_hi:[1,0,1]
	v_pk_fma_f32 v[212:213], v[122:123], v[180:181], v[90:91] op_sel_hi:[1,0,1]
	v_pk_fma_f32 v[206:207], v[128:129], v[180:181], v[96:97] op_sel_hi:[1,0,1]
	v_pk_fma_f32 v[204:205], v[126:127], v[180:181], v[94:95] op_sel_hi:[1,0,1]
	v_lshlrev_b64 v[188:189], 11, v[188:189]
	v_cvt_pk_bf16_f32 v204, v204, v205
	v_cvt_pk_bf16_f32 v205, v206, v207
	v_cvt_pk_bf16_f32 v206, v212, v213
	v_cvt_pk_bf16_f32 v207, v210, v211
	v_lshl_add_u64 v[210:211], v[208:209], 0, v[202:203]
	global_store_dwordx4 v[210:211], v[204:207], off
	v_pk_fma_f32 v[202:203], v[118:119], v[180:181], v[86:87] op_sel_hi:[1,0,1]
	v_pk_fma_f32 v[212:213], v[114:115], v[180:181], v[82:83] op_sel_hi:[1,0,1]
	v_pk_fma_f32 v[204:205], v[120:121], v[180:181], v[88:89] op_sel_hi:[1,0,1]
	v_pk_fma_f32 v[206:207], v[116:117], v[180:181], v[84:85] op_sel_hi:[1,0,1]
	v_cvt_pk_bf16_f32 v202, v202, v203
	v_cvt_pk_bf16_f32 v203, v204, v205
	v_cvt_pk_bf16_f32 v204, v212, v213
	v_lshl_add_u64 v[188:189], v[208:209], 0, v[188:189]
	v_cvt_pk_bf16_f32 v205, v206, v207
	global_store_dwordx4 v[210:211], v[202:205], off offset:256
	v_pk_fma_f32 v[206:207], v[108:109], v[176:177], v[92:93] op_sel_hi:[1,0,1]
	v_pk_fma_f32 v[210:211], v[106:107], v[176:177], v[90:91] op_sel_hi:[1,0,1]
	v_pk_fma_f32 v[204:205], v[112:113], v[176:177], v[96:97] op_sel_hi:[1,0,1]
	v_pk_fma_f32 v[202:203], v[110:111], v[176:177], v[94:95] op_sel_hi:[1,0,1]
	v_lshlrev_b64 v[184:185], 11, v[184:185]
	v_cvt_pk_bf16_f32 v202, v202, v203
	v_cvt_pk_bf16_f32 v203, v204, v205
	v_cvt_pk_bf16_f32 v204, v210, v211
	v_cvt_pk_bf16_f32 v205, v206, v207
	global_store_dwordx4 v[188:189], v[202:205], off
	v_pk_fma_f32 v[206:207], v[100:101], v[176:177], v[84:85] op_sel_hi:[1,0,1]
	v_pk_fma_f32 v[210:211], v[98:99], v[176:177], v[82:83] op_sel_hi:[1,0,1]
	v_pk_fma_f32 v[204:205], v[104:105], v[176:177], v[88:89] op_sel_hi:[1,0,1]
	v_pk_fma_f32 v[202:203], v[102:103], v[176:177], v[86:87] op_sel_hi:[1,0,1]
	v_lshl_add_u64 v[184:185], v[208:209], 0, v[184:185]
	v_cvt_pk_bf16_f32 v202, v202, v203
	v_cvt_pk_bf16_f32 v203, v204, v205
	v_cvt_pk_bf16_f32 v204, v210, v211
	v_cvt_pk_bf16_f32 v205, v206, v207
	global_store_dwordx4 v[188:189], v[202:205], off offset:256
	v_pk_fma_f32 v[188:189], v[80:81], v[174:175], v[96:97] op_sel_hi:[1,0,1]
	v_pk_fma_f32 v[206:207], v[76:77], v[174:175], v[92:93] op_sel_hi:[1,0,1]
	v_pk_fma_f32 v[202:203], v[78:79], v[174:175], v[94:95] op_sel_hi:[1,0,1]
	v_pk_fma_f32 v[204:205], v[74:75], v[174:175], v[90:91] op_sel_hi:[1,0,1]
	v_cvt_pk_bf16_f32 v202, v202, v203
	v_cvt_pk_bf16_f32 v203, v188, v189
	v_pk_fma_f32 v[188:189], v[72:73], v[174:175], v[88:89] op_sel_hi:[1,0,1]
	v_cvt_pk_bf16_f32 v204, v204, v205
	v_cvt_pk_bf16_f32 v205, v206, v207
	global_store_dwordx4 v[184:185], v[202:205], off
	v_pk_fma_f32 v[206:207], v[68:69], v[174:175], v[84:85] op_sel_hi:[1,0,1]
	v_lshlrev_b64 v[168:169], 11, v[168:169]
	v_pk_fma_f32 v[202:203], v[70:71], v[174:175], v[86:87] op_sel_hi:[1,0,1]
	v_pk_fma_f32 v[204:205], v[66:67], v[174:175], v[82:83] op_sel_hi:[1,0,1]
	v_cvt_pk_bf16_f32 v202, v202, v203
	v_cvt_pk_bf16_f32 v203, v188, v189
	v_pk_fma_f32 v[188:189], v[62:63], v[172:173], v[94:95] op_sel_hi:[1,0,1]
	v_cvt_pk_bf16_f32 v204, v204, v205
	v_cvt_pk_bf16_f32 v205, v206, v207
	global_store_dwordx4 v[184:185], v[202:205], off offset:256
	v_pk_fma_f32 v[184:185], v[64:65], v[172:173], v[96:97] op_sel_hi:[1,0,1]
	v_pk_fma_f32 v[206:207], v[60:61], v[172:173], v[92:93] op_sel_hi:[1,0,1]
	v_pk_fma_f32 v[204:205], v[58:59], v[172:173], v[90:91] op_sel_hi:[1,0,1]
	v_cvt_pk_bf16_f32 v202, v188, v189
	v_cvt_pk_bf16_f32 v203, v184, v185
	v_lshl_add_u64 v[168:169], v[208:209], 0, v[168:169]
	v_cvt_pk_bf16_f32 v204, v204, v205
	v_cvt_pk_bf16_f32 v205, v206, v207
	global_store_dwordx4 v[168:169], v[202:205], off
	v_pk_fma_f32 v[184:185], v[56:57], v[172:173], v[88:89] op_sel_hi:[1,0,1]
	v_pk_fma_f32 v[188:189], v[54:55], v[172:173], v[86:87] op_sel_hi:[1,0,1]
	v_pk_fma_f32 v[204:205], v[50:51], v[172:173], v[82:83] op_sel_hi:[1,0,1]
	v_pk_fma_f32 v[206:207], v[52:53], v[172:173], v[84:85] op_sel_hi:[1,0,1]
	v_cvt_pk_bf16_f32 v202, v188, v189
	v_cvt_pk_bf16_f32 v203, v184, v185
	v_cvt_pk_bf16_f32 v204, v204, v205
	s_mov_b64 s[0:1], 0x48000
	v_cvt_pk_bf16_f32 v205, v206, v207
	global_store_dwordx4 v[168:169], v[202:205], off offset:256
	v_pk_fma_f32 v[168:169], v[48:49], v[170:171], v[96:97] op_sel_hi:[1,0,1]
	v_pk_fma_f32 v[184:185], v[46:47], v[170:171], v[94:95] op_sel_hi:[1,0,1]
	v_pk_fma_f32 v[204:205], v[42:43], v[170:171], v[90:91] op_sel_hi:[1,0,1]
	v_cvt_pk_bf16_f32 v202, v184, v185
	v_cvt_pk_bf16_f32 v203, v168, v169
	v_lshl_add_u64 v[168:169], v[186:187], 0, s[0:1]
	s_mov_b32 s0, 0x48000
	v_add_co_u32_e32 v184, vcc, s0, v186
	v_pk_fma_f32 v[188:189], v[44:45], v[170:171], v[92:93] op_sel_hi:[1,0,1]
	v_cvt_pk_bf16_f32 v204, v204, v205
	s_nop 0
	v_addc_co_u32_e32 v185, vcc, 0, v187, vcc
	v_cvt_pk_bf16_f32 v205, v188, v189
	global_store_dwordx4 v[184:185], v[202:205], off
	v_pk_fma_f32 v[184:185], v[40:41], v[170:171], v[88:89] op_sel_hi:[1,0,1]
	v_pk_fma_f32 v[188:189], v[38:39], v[170:171], v[86:87] op_sel_hi:[1,0,1]
	v_pk_fma_f32 v[204:205], v[34:35], v[170:171], v[82:83] op_sel_hi:[1,0,1]
	v_pk_fma_f32 v[206:207], v[36:37], v[170:171], v[84:85] op_sel_hi:[1,0,1]
	v_cvt_pk_bf16_f32 v202, v188, v189
	v_cvt_pk_bf16_f32 v203, v184, v185
	v_cvt_pk_bf16_f32 v204, v204, v205
	s_mov_b64 s[0:1], 0x50000
	v_cvt_pk_bf16_f32 v205, v206, v207
	global_store_dwordx4 v[168:169], v[202:205], off offset:256
	v_pk_fma_f32 v[168:169], v[32:33], v[166:167], v[96:97] op_sel_hi:[1,0,1]
	v_pk_fma_f32 v[184:185], v[30:31], v[166:167], v[94:95] op_sel_hi:[1,0,1]
	v_pk_fma_f32 v[204:205], v[26:27], v[166:167], v[90:91] op_sel_hi:[1,0,1]
	v_cvt_pk_bf16_f32 v202, v184, v185
	v_cvt_pk_bf16_f32 v203, v168, v169
	v_lshl_add_u64 v[168:169], v[186:187], 0, s[0:1]
	s_mov_b32 s0, 0x50000
	v_add_co_u32_e32 v184, vcc, s0, v186
	v_pk_fma_f32 v[188:189], v[28:29], v[166:167], v[92:93] op_sel_hi:[1,0,1]
	v_cvt_pk_bf16_f32 v204, v204, v205
	s_nop 0
	v_addc_co_u32_e32 v185, vcc, 0, v187, vcc
	v_cvt_pk_bf16_f32 v205, v188, v189
	global_store_dwordx4 v[184:185], v[202:205], off
	v_pk_fma_f32 v[184:185], v[24:25], v[166:167], v[88:89] op_sel_hi:[1,0,1]
	v_pk_fma_f32 v[188:189], v[22:23], v[166:167], v[86:87] op_sel_hi:[1,0,1]
	v_pk_fma_f32 v[204:205], v[18:19], v[166:167], v[82:83] op_sel_hi:[1,0,1]
	v_pk_fma_f32 v[206:207], v[20:21], v[166:167], v[84:85] op_sel_hi:[1,0,1]
	v_cvt_pk_bf16_f32 v202, v188, v189
	v_cvt_pk_bf16_f32 v203, v184, v185
	v_cvt_pk_bf16_f32 v204, v204, v205
	s_mov_b64 s[0:1], 0x58000
	v_cvt_pk_bf16_f32 v205, v206, v207
	global_store_dwordx4 v[168:169], v[202:205], off offset:256
	v_pk_fma_f32 v[168:169], v[16:17], v[164:165], v[96:97] op_sel_hi:[1,0,1]
	v_pk_fma_f32 v[184:185], v[14:15], v[164:165], v[94:95] op_sel_hi:[1,0,1]
	v_pk_fma_f32 v[204:205], v[10:11], v[164:165], v[90:91] op_sel_hi:[1,0,1]
	v_cvt_pk_bf16_f32 v202, v184, v185
	v_cvt_pk_bf16_f32 v203, v168, v169
	v_lshl_add_u64 v[168:169], v[186:187], 0, s[0:1]
	s_mov_b32 s0, 0x58000
	v_add_co_u32_e32 v184, vcc, s0, v186
	v_pk_fma_f32 v[188:189], v[12:13], v[164:165], v[92:93] op_sel_hi:[1,0,1]
	s_nop 0
	v_addc_co_u32_e32 v185, vcc, 0, v187, vcc
	v_cvt_pk_bf16_f32 v204, v204, v205
	v_cvt_pk_bf16_f32 v205, v188, v189
	global_store_dwordx4 v[184:185], v[202:205], off
	v_pk_fma_f32 v[186:187], v[8:9], v[164:165], v[88:89] op_sel_hi:[1,0,1]
	v_pk_fma_f32 v[184:185], v[6:7], v[164:165], v[86:87] op_sel_hi:[1,0,1]
	v_pk_fma_f32 v[188:189], v[4:5], v[164:165], v[84:85] op_sel_hi:[1,0,1]
	v_pk_fma_f32 v[202:203], v[2:3], v[164:165], v[82:83] op_sel_hi:[1,0,1]
	v_cvt_pk_bf16_f32 v184, v184, v185
	v_cvt_pk_bf16_f32 v185, v186, v187
	s_nop 0
	v_cvt_pk_bf16_f32 v186, v202, v203
	v_cvt_pk_bf16_f32 v187, v188, v189
	global_store_dwordx4 v[168:169], v[184:187], off offset:256
	s_cbranch_execz .LBB0_469

	.amdhsa_kernel _Z14fwd_megakernel6Params
		.amdhsa_group_segment_fixed_size 8192
		.amdhsa_private_segment_fixed_size 0
		.amdhsa_kernarg_size 504
		.amdhsa_user_sgpr_count 2
		.amdhsa_user_sgpr_dispatch_ptr 0
		.amdhsa_user_sgpr_queue_ptr 0
		.amdhsa_user_sgpr_kernarg_segment_ptr 1
		.amdhsa_user_sgpr_dispatch_id 0
		.amdhsa_user_sgpr_kernarg_preload_length 0
		.amdhsa_user_sgpr_kernarg_preload_offset 0
		.amdhsa_user_sgpr_private_segment_size 0
		.amdhsa_uses_dynamic_stack 0
		.amdhsa_enable_private_segment 0
		.amdhsa_system_sgpr_workgroup_id_x 1
		.amdhsa_system_sgpr_workgroup_id_y 0
		.amdhsa_system_sgpr_workgroup_id_z 0
		.amdhsa_system_sgpr_workgroup_info 0
		.amdhsa_system_vgpr_workitem_id 2
		.amdhsa_next_free_vgpr 256
		.amdhsa_next_free_sgpr 100
		.amdhsa_accum_offset 256
		.amdhsa_reserve_vcc 1
		.amdhsa_float_round_mode_32 0
		.amdhsa_float_round_mode_16_64 0
		.amdhsa_float_denorm_mode_32 3
		.amdhsa_float_denorm_mode_16_64 3
		.amdhsa_dx10_clamp 1
		.amdhsa_ieee_mode 1
		.amdhsa_fp16_overflow 0
		.amdhsa_tg_split 0
		.amdhsa_exception_fp_ieee_invalid_op 0
		.amdhsa_exception_fp_denorm_src 0
		.amdhsa_exception_fp_ieee_div_zero 0
		.amdhsa_exception_fp_ieee_overflow 0
		.amdhsa_exception_fp_ieee_underflow 0
		.amdhsa_exception_fp_ieee_inexact 0
		.amdhsa_exception_int_div_zero 0
	.end_amdhsa_kernel

amdhsa.kernels:
  - .agpr_count:     0
    .args:
      - .offset:         0
        .size:           248
        .value_kind:     by_value
      - .offset:         248
        .size:           4
        .value_kind:     hidden_block_count_x
      - .offset:         252
        .size:           4
        .value_kind:     hidden_block_count_y
      - .offset:         256
        .size:           4
        .value_kind:     hidden_block_count_z
      - .offset:         260
        .size:           2
        .value_kind:     hidden_group_size_x
      - .offset:         262
        .size:           2
        .value_kind:     hidden_group_size_y
      - .offset:         264
        .size:           2
        .value_kind:     hidden_group_size_z
      - .offset:         266
        .size:           2
        .value_kind:     hidden_remainder_x
      - .offset:         268
        .size:           2
        .value_kind:     hidden_remainder_y
      - .offset:         270
        .size:           2
        .value_kind:     hidden_remainder_z
      - .offset:         288
        .size:           8
        .value_kind:     hidden_global_offset_x
      - .offset:         296
        .size:           8
        .value_kind:     hidden_global_offset_y
      - .offset:         304
        .size:           8
        .value_kind:     hidden_global_offset_z
      - .offset:         312
        .size:           2
        .value_kind:     hidden_grid_dims
      - .offset:         336
        .size:           8
        .value_kind:     hidden_multigrid_sync_arg
      - .offset:         368
        .size:           4
        .value_kind:     hidden_dynamic_lds_size
    .group_segment_fixed_size: 8192
    .kernarg_segment_align: 8
    .kernarg_segment_size: 504
    .language:       OpenCL C
    .language_version:
      - 2
      - 0
    .max_flat_workgroup_size: 512
    .name:           _Z14fwd_megakernel6Params
    .private_segment_fixed_size: 0
    .sgpr_count:     106
    .sgpr_spill_count: 65
    .symbol:         _Z14fwd_megakernel6Params.kd
    .uniform_work_group_size: 1
    .uses_dynamic_stack: false
    .vgpr_count:     256
    .vgpr_spill_count: 0
    .wavefront_size: 64
